# kv up-projection epilogue rewritten by hand: all row-statistic and shared-rope-key loads issued once up front, permlane reductions, packed f32 scaling, running store pointers
# speedup vs baseline: 1.0058x; 1.0058x over previous
.LBB0_953:
	s_cmp_lt_i32 s66, 3
	s_mov_b64 s[0:1], -1
	s_cbranch_scc1 .LBB0_1091
	s_cmp_gt_i32 s66, 3
	s_cbranch_scc0 .LBB0_1088
	s_waitcnt lgkmcnt(0)
	v_and_b32_e32 v80, 15, v192
	v_ashrrev_i32_e32 v82, 2, v192
	s_movk_i32 s0, 0xffc0
	v_and_or_b32 v145, v82, s0, v80
	v_bfe_u32 v144, v192, 6, 2
	v_bfe_u32 v146, v192, 4, 2
	v_add_u32_e32 v148, s30, v145
	v_ashrrev_i32_e32 v149, 31, v148
	v_lshl_add_u64 v[82:83], v[148:149], 2, s[90:91]
	s_mov_b64 s[10:11], 0xa0000
	s_nop 0
	v_lshl_add_u64 v[140:141], v[82:83], 0, s[10:11]
	s_mov_b64 s[10:11], 0x100000
	s_nop 0
	v_lshl_add_u64 v[142:143], v[82:83], 0, s[10:11]
	global_load_dword v204, v[140:141], off
	global_load_dword v205, v[140:141], off offset:64
	global_load_dword v206, v[140:141], off offset:128
	global_load_dword v207, v[140:141], off offset:192
	global_load_dword v208, v[140:141], off offset:512
	global_load_dword v209, v[140:141], off offset:576
	global_load_dword v210, v[140:141], off offset:640
	global_load_dword v211, v[140:141], off offset:704
	global_load_dword v132, v[142:143], off
	global_load_dword v133, v[142:143], off offset:64
	global_load_dword v134, v[142:143], off offset:128
	global_load_dword v135, v[142:143], off offset:192
	global_load_dword v136, v[142:143], off offset:512
	global_load_dword v137, v[142:143], off offset:576
	global_load_dword v138, v[142:143], off offset:640
	global_load_dword v139, v[142:143], off offset:704
	v_cmp_eq_u32_e64 s[40:41], 0, v146
	v_readfirstlane_b32 s37, v144
	v_ashrrev_i32_e32 v150, 9, v148
	v_and_b32_e32 v150, -8, v150
	s_ashr_i32 s7, s6, 7
	v_add_u32_e32 v150, s7, v150
	v_lshlrev_b32_e32 v150, 12, v150
	v_and_b32_e32 v151, 0xfff, v148
	v_or_b32_e32 v150, v150, v151
	v_mul_u32_u24_e32 v150, 0xc0, v150
	v_lshlrev_b32_e32 v151, 4, v146
	v_add_u32_e32 v150, v150, v151
	v_mov_b32_e32 v151, v81
	v_lshl_add_u64 v[150:151], v[150:151], 0, s[58:59]
	v_lshl_add_u32 v147, v145, 4, 16
	s_cmp_lt_u32 s37, 2
	s_cbranch_scc1 .Lkv_p1
	v_readlane_b32 s42, v253, 12
	v_lshlrev_b64 v[244:245], 6, v[148:149]
	v_readlane_b32 s43, v253, 13
	v_lshlrev_b32_e32 v246, 4, v146
	v_mov_b32_e32 v247, v81
	v_lshl_add_u64 v[244:245], s[42:43], 0, v[244:245]
	v_lshl_add_u64 v[244:245], v[244:245], 0, v[246:247]
	s_mov_b64 s[10:11], 0x2000
	s_nop 0
	v_lshl_add_u64 v[246:247], v[244:245], 0, s[10:11]
	global_load_dwordx4 v[160:163], v[244:245], off
	global_load_dwordx4 v[164:167], v[244:245], off offset:1024
	global_load_dwordx4 v[168:171], v[244:245], off offset:2048
	global_load_dwordx4 v[172:175], v[244:245], off offset:3072
	global_load_dwordx4 v[176:179], v[246:247], off
	global_load_dwordx4 v[180:183], v[246:247], off offset:1024
	global_load_dwordx4 v[184:187], v[246:247], off offset:2048
	global_load_dwordx4 v[188:191], v[246:247], off offset:3072
	v_readlane_b32 s10, v252, 22
	v_lshlrev_b64 v[248:249], 11, v[148:149]
	v_readlane_b32 s11, v252, 23
	v_lshl_add_u32 v250, v144, 5, s6
	v_lshl_add_u32 v250, v146, 3, v250
	v_lshlrev_b32_e32 v250, 1, v250
	v_lshl_add_u64 v[248:249], s[10:11], 0, v[248:249]
	v_mov_b32_e32 v83, v81
	v_mov_b32_e32 v82, v250
	v_lshl_add_u64 v[248:249], v[248:249], 0, v[82:83]
	s_sub_u32 s7, s37, 2
	s_mul_i32 s10, s7, 0xc0000
	s_add_u32 s10, s10, 0x80
	s_mov_b32 s11, 0
	v_lshl_add_u64 v[150:151], v[150:151], 0, s[10:11]
	s_lshl_b32 s7, s7, 3
	v_add_u32_e32 v147, s7, v147
	s_waitcnt vmcnt(16)
	v_fmamk_f32 v204, v204, 0x3b800000, v194
	v_fmamk_f32 v205, v205, 0x3b800000, v194
	v_fmamk_f32 v206, v206, 0x3b800000, v194
	v_fmamk_f32 v207, v207, 0x3b800000, v194
	v_fmamk_f32 v208, v208, 0x3b800000, v194
	v_fmamk_f32 v209, v209, 0x3b800000, v194
	v_fmamk_f32 v210, v210, 0x3b800000, v194
	v_fmamk_f32 v211, v211, 0x3b800000, v194
	v_rsq_f32_e32 v204, v204
	v_rsq_f32_e32 v205, v205
	v_rsq_f32_e32 v206, v206
	v_rsq_f32_e32 v207, v207
	v_rsq_f32_e32 v208, v208
	v_rsq_f32_e32 v209, v209
	v_rsq_f32_e32 v210, v210
	v_rsq_f32_e32 v211, v211
	s_branch .Lkv_bar
.Lkv_p1:
	v_lshl_add_u32 v248, v144, 2, v147
	s_waitcnt vmcnt(8)
	v_fmamk_f32 v204, v204, 0x3b800000, v194
	v_fmamk_f32 v205, v205, 0x3b800000, v194
	v_fmamk_f32 v206, v206, 0x3b800000, v194
	v_fmamk_f32 v207, v207, 0x3b800000, v194
	v_fmamk_f32 v208, v208, 0x3b800000, v194
	v_fmamk_f32 v209, v209, 0x3b800000, v194
	v_fmamk_f32 v210, v210, 0x3b800000, v194
	v_fmamk_f32 v211, v211, 0x3b800000, v194
	v_rsq_f32_e32 v204, v204
	v_rsq_f32_e32 v205, v205
	v_rsq_f32_e32 v206, v206
	v_rsq_f32_e32 v207, v207
	v_rsq_f32_e32 v208, v208
	v_rsq_f32_e32 v209, v209
	v_rsq_f32_e32 v210, v210
	v_rsq_f32_e32 v211, v211
	v_mul_f32_e32 v250, v204, v204
	v_pk_mul_f32 v[244:245], v[128:129], v[128:129]
	v_pk_fma_f32 v[244:245], v[130:131], v[130:131], v[244:245]
	v_pk_fma_f32 v[244:245], v[124:125], v[124:125], v[244:245]
	v_pk_fma_f32 v[244:245], v[126:127], v[126:127], v[244:245]
	v_add_f32_e32 v246, v244, v245
	v_mul_f32_e32 v246, v246, v250
	v_mov_b32_e32 v247, v246
	s_nop 1
	v_permlane32_swap_b32 v247, v246
	s_nop 1
	v_add_f32_e32 v246, v246, v247
	v_mov_b32_e32 v247, v246
	s_nop 1
	v_permlane16_swap_b32 v247, v246
	s_nop 1
	v_add_f32_e32 v246, v246, v247
	s_mov_b64 exec, s[40:41]
	ds_write_b32 v248, v246 offset:32768
	s_mov_b64 exec, -1
	v_pk_mul_f32 v[244:245], v[120:121], v[120:121]
	v_pk_fma_f32 v[244:245], v[122:123], v[122:123], v[244:245]
	v_pk_fma_f32 v[244:245], v[116:117], v[116:117], v[244:245]
	v_pk_fma_f32 v[244:245], v[118:119], v[118:119], v[244:245]
	v_add_f32_e32 v246, v244, v245
	v_mul_f32_e32 v246, v246, v250
	v_mov_b32_e32 v247, v246
	s_nop 1
	v_permlane32_swap_b32 v247, v246
	s_nop 1
	v_add_f32_e32 v246, v246, v247
	v_mov_b32_e32 v247, v246
	s_nop 1
	v_permlane16_swap_b32 v247, v246
	s_nop 1
	v_add_f32_e32 v246, v246, v247
	s_mov_b64 exec, s[40:41]
	ds_write_b32 v248, v246 offset:32776
	s_mov_b64 exec, -1
	v_mul_f32_e32 v250, v205, v205
	v_pk_mul_f32 v[244:245], v[112:113], v[112:113]
	v_pk_fma_f32 v[244:245], v[114:115], v[114:115], v[244:245]
	v_pk_fma_f32 v[244:245], v[108:109], v[108:109], v[244:245]
	v_pk_fma_f32 v[244:245], v[110:111], v[110:111], v[244:245]
	v_add_f32_e32 v246, v244, v245
	v_mul_f32_e32 v246, v246, v250
	v_mov_b32_e32 v247, v246
	s_nop 1
	v_permlane32_swap_b32 v247, v246
	s_nop 1
	v_add_f32_e32 v246, v246, v247
	v_mov_b32_e32 v247, v246
	s_nop 1
	v_permlane16_swap_b32 v247, v246
	s_nop 1
	v_add_f32_e32 v246, v246, v247
	s_mov_b64 exec, s[40:41]
	ds_write_b32 v248, v246 offset:33024
	s_mov_b64 exec, -1
	v_pk_mul_f32 v[244:245], v[104:105], v[104:105]
	v_pk_fma_f32 v[244:245], v[106:107], v[106:107], v[244:245]
	v_pk_fma_f32 v[244:245], v[100:101], v[100:101], v[244:245]
	v_pk_fma_f32 v[244:245], v[102:103], v[102:103], v[244:245]
	v_add_f32_e32 v246, v244, v245
	v_mul_f32_e32 v246, v246, v250
	v_mov_b32_e32 v247, v246
	s_nop 1
	v_permlane32_swap_b32 v247, v246
	s_nop 1
	v_add_f32_e32 v246, v246, v247
	v_mov_b32_e32 v247, v246
	s_nop 1
	v_permlane16_swap_b32 v247, v246
	s_nop 1
	v_add_f32_e32 v246, v246, v247
	s_mov_b64 exec, s[40:41]
	ds_write_b32 v248, v246 offset:33032
	s_mov_b64 exec, -1
	v_mul_f32_e32 v250, v206, v206
	v_pk_mul_f32 v[244:245], v[96:97], v[96:97]
	v_pk_fma_f32 v[244:245], v[98:99], v[98:99], v[244:245]
	v_pk_fma_f32 v[244:245], v[92:93], v[92:93], v[244:245]
	v_pk_fma_f32 v[244:245], v[94:95], v[94:95], v[244:245]
	v_add_f32_e32 v246, v244, v245
	v_mul_f32_e32 v246, v246, v250
	v_mov_b32_e32 v247, v246
	s_nop 1
	v_permlane32_swap_b32 v247, v246
	s_nop 1
	v_add_f32_e32 v246, v246, v247
	v_mov_b32_e32 v247, v246
	s_nop 1
	v_permlane16_swap_b32 v247, v246
	s_nop 1
	v_add_f32_e32 v246, v246, v247
	s_mov_b64 exec, s[40:41]
	ds_write_b32 v248, v246 offset:33280
	s_mov_b64 exec, -1
	v_pk_mul_f32 v[244:245], v[88:89], v[88:89]
	v_pk_fma_f32 v[244:245], v[90:91], v[90:91], v[244:245]
	v_pk_fma_f32 v[244:245], v[84:85], v[84:85], v[244:245]
	v_pk_fma_f32 v[244:245], v[86:87], v[86:87], v[244:245]
	v_add_f32_e32 v246, v244, v245
	v_mul_f32_e32 v246, v246, v250
	v_mov_b32_e32 v247, v246
	s_nop 1
	v_permlane32_swap_b32 v247, v246
	s_nop 1
	v_add_f32_e32 v246, v246, v247
	v_mov_b32_e32 v247, v246
	s_nop 1
	v_permlane16_swap_b32 v247, v246
	s_nop 1
	v_add_f32_e32 v246, v246, v247
	s_mov_b64 exec, s[40:41]
	ds_write_b32 v248, v246 offset:33288
	s_mov_b64 exec, -1
	v_mul_f32_e32 v250, v207, v207
	v_pk_mul_f32 v[244:245], v[76:77], v[76:77]
	v_pk_fma_f32 v[244:245], v[78:79], v[78:79], v[244:245]
	v_pk_fma_f32 v[244:245], v[72:73], v[72:73], v[244:245]
	v_pk_fma_f32 v[244:245], v[74:75], v[74:75], v[244:245]
	v_add_f32_e32 v246, v244, v245
	v_mul_f32_e32 v246, v246, v250
	v_mov_b32_e32 v247, v246
	s_nop 1
	v_permlane32_swap_b32 v247, v246
	s_nop 1
	v_add_f32_e32 v246, v246, v247
	v_mov_b32_e32 v247, v246
	s_nop 1
	v_permlane16_swap_b32 v247, v246
	s_nop 1
	v_add_f32_e32 v246, v246, v247
	s_mov_b64 exec, s[40:41]
	ds_write_b32 v248, v246 offset:33536
	s_mov_b64 exec, -1
	v_pk_mul_f32 v[244:245], v[68:69], v[68:69]
	v_pk_fma_f32 v[244:245], v[70:71], v[70:71], v[244:245]
	v_pk_fma_f32 v[244:245], v[64:65], v[64:65], v[244:245]
	v_pk_fma_f32 v[244:245], v[66:67], v[66:67], v[244:245]
	v_add_f32_e32 v246, v244, v245
	v_mul_f32_e32 v246, v246, v250
	v_mov_b32_e32 v247, v246
	s_nop 1
	v_permlane32_swap_b32 v247, v246
	s_nop 1
	v_add_f32_e32 v246, v246, v247
	v_mov_b32_e32 v247, v246
	s_nop 1
	v_permlane16_swap_b32 v247, v246
	s_nop 1
	v_add_f32_e32 v246, v246, v247
	s_mov_b64 exec, s[40:41]
	ds_write_b32 v248, v246 offset:33544
	s_mov_b64 exec, -1
	v_mul_f32_e32 v250, v208, v208
	v_pk_mul_f32 v[244:245], v[60:61], v[60:61]
	v_pk_fma_f32 v[244:245], v[62:63], v[62:63], v[244:245]
	v_pk_fma_f32 v[244:245], v[56:57], v[56:57], v[244:245]
	v_pk_fma_f32 v[244:245], v[58:59], v[58:59], v[244:245]
	v_add_f32_e32 v246, v244, v245
	v_mul_f32_e32 v246, v246, v250
	v_mov_b32_e32 v247, v246
	s_nop 1
	v_permlane32_swap_b32 v247, v246
	s_nop 1
	v_add_f32_e32 v246, v246, v247
	v_mov_b32_e32 v247, v246
	s_nop 1
	v_permlane16_swap_b32 v247, v246
	s_nop 1
	v_add_f32_e32 v246, v246, v247
	s_mov_b64 exec, s[40:41]
	ds_write_b32 v248, v246 offset:34816
	s_mov_b64 exec, -1
	v_pk_mul_f32 v[244:245], v[52:53], v[52:53]
	v_pk_fma_f32 v[244:245], v[54:55], v[54:55], v[244:245]
	v_pk_fma_f32 v[244:245], v[48:49], v[48:49], v[244:245]
	v_pk_fma_f32 v[244:245], v[50:51], v[50:51], v[244:245]
	v_add_f32_e32 v246, v244, v245
	v_mul_f32_e32 v246, v246, v250
	v_mov_b32_e32 v247, v246
	s_nop 1
	v_permlane32_swap_b32 v247, v246
	s_nop 1
	v_add_f32_e32 v246, v246, v247
	v_mov_b32_e32 v247, v246
	s_nop 1
	v_permlane16_swap_b32 v247, v246
	s_nop 1
	v_add_f32_e32 v246, v246, v247
	s_mov_b64 exec, s[40:41]
	ds_write_b32 v248, v246 offset:34824
	s_mov_b64 exec, -1
	v_mul_f32_e32 v250, v209, v209
	v_pk_mul_f32 v[244:245], v[44:45], v[44:45]
	v_pk_fma_f32 v[244:245], v[46:47], v[46:47], v[244:245]
	v_pk_fma_f32 v[244:245], v[40:41], v[40:41], v[244:245]
	v_pk_fma_f32 v[244:245], v[42:43], v[42:43], v[244:245]
	v_add_f32_e32 v246, v244, v245
	v_mul_f32_e32 v246, v246, v250
	v_mov_b32_e32 v247, v246
	s_nop 1
	v_permlane32_swap_b32 v247, v246
	s_nop 1
	v_add_f32_e32 v246, v246, v247
	v_mov_b32_e32 v247, v246
	s_nop 1
	v_permlane16_swap_b32 v247, v246
	s_nop 1
	v_add_f32_e32 v246, v246, v247
	s_mov_b64 exec, s[40:41]
	ds_write_b32 v248, v246 offset:35072
	s_mov_b64 exec, -1
	v_pk_mul_f32 v[244:245], v[36:37], v[36:37]
	v_pk_fma_f32 v[244:245], v[38:39], v[38:39], v[244:245]
	v_pk_fma_f32 v[244:245], v[32:33], v[32:33], v[244:245]
	v_pk_fma_f32 v[244:245], v[34:35], v[34:35], v[244:245]
	v_add_f32_e32 v246, v244, v245
	v_mul_f32_e32 v246, v246, v250
	v_mov_b32_e32 v247, v246
	s_nop 1
	v_permlane32_swap_b32 v247, v246
	s_nop 1
	v_add_f32_e32 v246, v246, v247
	v_mov_b32_e32 v247, v246
	s_nop 1
	v_permlane16_swap_b32 v247, v246
	s_nop 1
	v_add_f32_e32 v246, v246, v247
	s_mov_b64 exec, s[40:41]
	ds_write_b32 v248, v246 offset:35080
	s_mov_b64 exec, -1
	v_mul_f32_e32 v250, v210, v210
	v_pk_mul_f32 v[244:245], v[28:29], v[28:29]
	v_pk_fma_f32 v[244:245], v[30:31], v[30:31], v[244:245]
	v_pk_fma_f32 v[244:245], v[24:25], v[24:25], v[244:245]
	v_pk_fma_f32 v[244:245], v[26:27], v[26:27], v[244:245]
	v_add_f32_e32 v246, v244, v245
	v_mul_f32_e32 v246, v246, v250
	v_mov_b32_e32 v247, v246
	s_nop 1
	v_permlane32_swap_b32 v247, v246
	s_nop 1
	v_add_f32_e32 v246, v246, v247
	v_mov_b32_e32 v247, v246
	s_nop 1
	v_permlane16_swap_b32 v247, v246
	s_nop 1
	v_add_f32_e32 v246, v246, v247
	s_mov_b64 exec, s[40:41]
	ds_write_b32 v248, v246 offset:35328
	s_mov_b64 exec, -1
	v_pk_mul_f32 v[244:245], v[20:21], v[20:21]
	v_pk_fma_f32 v[244:245], v[22:23], v[22:23], v[244:245]
	v_pk_fma_f32 v[244:245], v[16:17], v[16:17], v[244:245]
	v_pk_fma_f32 v[244:245], v[18:19], v[18:19], v[244:245]
	v_add_f32_e32 v246, v244, v245
	v_mul_f32_e32 v246, v246, v250
	v_mov_b32_e32 v247, v246
	s_nop 1
	v_permlane32_swap_b32 v247, v246
	s_nop 1
	v_add_f32_e32 v246, v246, v247
	v_mov_b32_e32 v247, v246
	s_nop 1
	v_permlane16_swap_b32 v247, v246
	s_nop 1
	v_add_f32_e32 v246, v246, v247
	s_mov_b64 exec, s[40:41]
	ds_write_b32 v248, v246 offset:35336
	s_mov_b64 exec, -1
	v_mul_f32_e32 v250, v211, v211
	v_pk_mul_f32 v[244:245], v[12:13], v[12:13]
	v_pk_fma_f32 v[244:245], v[14:15], v[14:15], v[244:245]
	v_pk_fma_f32 v[244:245], v[8:9], v[8:9], v[244:245]
	v_pk_fma_f32 v[244:245], v[10:11], v[10:11], v[244:245]
	v_add_f32_e32 v246, v244, v245
	v_mul_f32_e32 v246, v246, v250
	v_mov_b32_e32 v247, v246
	s_nop 1
	v_permlane32_swap_b32 v247, v246
	s_nop 1
	v_add_f32_e32 v246, v246, v247
	v_mov_b32_e32 v247, v246
	s_nop 1
	v_permlane16_swap_b32 v247, v246
	s_nop 1
	v_add_f32_e32 v246, v246, v247
	s_mov_b64 exec, s[40:41]
	ds_write_b32 v248, v246 offset:35584
	s_mov_b64 exec, -1
	v_pk_mul_f32 v[244:245], v[4:5], v[4:5]
	v_pk_fma_f32 v[244:245], v[6:7], v[6:7], v[244:245]
	v_pk_fma_f32 v[244:245], v[0:1], v[0:1], v[244:245]
	v_pk_fma_f32 v[244:245], v[2:3], v[2:3], v[244:245]
	v_add_f32_e32 v246, v244, v245
	v_mul_f32_e32 v246, v246, v250
	v_mov_b32_e32 v247, v246
	s_nop 1
	v_permlane32_swap_b32 v247, v246
	s_nop 1
	v_add_f32_e32 v246, v246, v247
	v_mov_b32_e32 v247, v246
	s_nop 1
	v_permlane16_swap_b32 v247, v246
	s_nop 1
	v_add_f32_e32 v246, v246, v247
	s_mov_b64 exec, s[40:41]
	ds_write_b32 v248, v246 offset:35592
	s_mov_b64 exec, -1
	s_lshl_b32 s10, s37, 6
	s_mov_b32 s11, 0
	v_lshl_add_u64 v[150:151], v[150:151], 0, s[10:11]
	s_mov_b64 s[10:11], 0xc0000
	s_nop 0
	v_lshl_add_u64 v[248:249], v[150:151], 0, s[10:11]
.Lkv_bar:
	s_waitcnt vmcnt(0) lgkmcnt(0)
	s_barrier
	s_cmp_lt_u32 s37, 2
	s_cbranch_scc0 .Lkv_v
	ds_read_b64 v[212:213], v147 offset:32768
	ds_read_b64 v[214:215], v147 offset:32776
	ds_read_b64 v[216:217], v147 offset:33024
	ds_read_b64 v[218:219], v147 offset:33032
	ds_read_b64 v[220:221], v147 offset:33280
	ds_read_b64 v[222:223], v147 offset:33288
	ds_read_b64 v[224:225], v147 offset:33536
	ds_read_b64 v[226:227], v147 offset:33544
	ds_read_b64 v[228:229], v147 offset:34816
	ds_read_b64 v[230:231], v147 offset:34824
	ds_read_b64 v[232:233], v147 offset:35072
	ds_read_b64 v[234:235], v147 offset:35080
	ds_read_b64 v[236:237], v147 offset:35328
	ds_read_b64 v[238:239], v147 offset:35336
	ds_read_b64 v[240:241], v147 offset:35584
	ds_read_b64 v[242:243], v147 offset:35592
	s_waitcnt lgkmcnt(0)
	v_add_f32_e32 v244, v212, v213
	v_add_f32_e32 v244, v244, v132
	v_fmamk_f32 v244, v244, 0x3c2aaaab, v194
	v_rsq_f32_e32 v244, v244
	s_nop 0
	v_mul_f32_e32 v244, v244, v204
	v_pk_mul_f32 v[128:129], v[128:129], v[244:245] op_sel_hi:[1,0]
	v_pk_mul_f32 v[130:131], v[130:131], v[244:245] op_sel_hi:[1,0]
	v_pk_mul_f32 v[124:125], v[124:125], v[244:245] op_sel_hi:[1,0]
	v_pk_mul_f32 v[126:127], v[126:127], v[244:245] op_sel_hi:[1,0]
	v_cvt_pk_bf16_f32 v128, v128, v129
	v_cvt_pk_bf16_f32 v129, v130, v131
	v_cvt_pk_bf16_f32 v130, v124, v125
	v_cvt_pk_bf16_f32 v131, v126, v127
	global_store_dwordx4 v[150:151], v[128:131], off
	v_add_f32_e32 v244, v214, v215
	v_add_f32_e32 v244, v244, v132
	v_fmamk_f32 v244, v244, 0x3c2aaaab, v194
	v_rsq_f32_e32 v244, v244
	s_nop 0
	v_mul_f32_e32 v244, v244, v204
	v_pk_mul_f32 v[120:121], v[120:121], v[244:245] op_sel_hi:[1,0]
	v_pk_mul_f32 v[122:123], v[122:123], v[244:245] op_sel_hi:[1,0]
	v_pk_mul_f32 v[116:117], v[116:117], v[244:245] op_sel_hi:[1,0]
	v_pk_mul_f32 v[118:119], v[118:119], v[244:245] op_sel_hi:[1,0]
	v_cvt_pk_bf16_f32 v120, v120, v121
	v_cvt_pk_bf16_f32 v121, v122, v123
	v_cvt_pk_bf16_f32 v122, v116, v117
	v_cvt_pk_bf16_f32 v123, v118, v119
	global_store_dwordx4 v[248:249], v[120:123], off
	s_mov_b64 vcc, 0xc00
	s_nop 0
	v_lshl_add_u64 v[150:151], v[150:151], 0, vcc
	v_lshl_add_u64 v[248:249], v[248:249], 0, vcc
	v_add_f32_e32 v244, v216, v217
	v_add_f32_e32 v244, v244, v133
	v_fmamk_f32 v244, v244, 0x3c2aaaab, v194
	v_rsq_f32_e32 v244, v244
	s_nop 0
	v_mul_f32_e32 v244, v244, v205
	v_pk_mul_f32 v[112:113], v[112:113], v[244:245] op_sel_hi:[1,0]
	v_pk_mul_f32 v[114:115], v[114:115], v[244:245] op_sel_hi:[1,0]
	v_pk_mul_f32 v[108:109], v[108:109], v[244:245] op_sel_hi:[1,0]
	v_pk_mul_f32 v[110:111], v[110:111], v[244:245] op_sel_hi:[1,0]
	v_cvt_pk_bf16_f32 v112, v112, v113
	v_cvt_pk_bf16_f32 v113, v114, v115
	v_cvt_pk_bf16_f32 v114, v108, v109
	v_cvt_pk_bf16_f32 v115, v110, v111
	global_store_dwordx4 v[150:151], v[112:115], off
	v_add_f32_e32 v244, v218, v219
	v_add_f32_e32 v244, v244, v133
	v_fmamk_f32 v244, v244, 0x3c2aaaab, v194
	v_rsq_f32_e32 v244, v244
	s_nop 0
	v_mul_f32_e32 v244, v244, v205
	v_pk_mul_f32 v[104:105], v[104:105], v[244:245] op_sel_hi:[1,0]
	v_pk_mul_f32 v[106:107], v[106:107], v[244:245] op_sel_hi:[1,0]
	v_pk_mul_f32 v[100:101], v[100:101], v[244:245] op_sel_hi:[1,0]
	v_pk_mul_f32 v[102:103], v[102:103], v[244:245] op_sel_hi:[1,0]
	v_cvt_pk_bf16_f32 v104, v104, v105
	v_cvt_pk_bf16_f32 v105, v106, v107
	v_cvt_pk_bf16_f32 v106, v100, v101
	v_cvt_pk_bf16_f32 v107, v102, v103
	global_store_dwordx4 v[248:249], v[104:107], off
	s_mov_b64 vcc, 0xc00
	s_nop 0
	v_lshl_add_u64 v[150:151], v[150:151], 0, vcc
	v_lshl_add_u64 v[248:249], v[248:249], 0, vcc
	v_add_f32_e32 v244, v220, v221
	v_add_f32_e32 v244, v244, v134
	v_fmamk_f32 v244, v244, 0x3c2aaaab, v194
	v_rsq_f32_e32 v244, v244
	s_nop 0
	v_mul_f32_e32 v244, v244, v206
	v_pk_mul_f32 v[96:97], v[96:97], v[244:245] op_sel_hi:[1,0]
	v_pk_mul_f32 v[98:99], v[98:99], v[244:245] op_sel_hi:[1,0]
	v_pk_mul_f32 v[92:93], v[92:93], v[244:245] op_sel_hi:[1,0]
	v_pk_mul_f32 v[94:95], v[94:95], v[244:245] op_sel_hi:[1,0]
	v_cvt_pk_bf16_f32 v96, v96, v97
	v_cvt_pk_bf16_f32 v97, v98, v99
	v_cvt_pk_bf16_f32 v98, v92, v93
	v_cvt_pk_bf16_f32 v99, v94, v95
	global_store_dwordx4 v[150:151], v[96:99], off
	v_add_f32_e32 v244, v222, v223
	v_add_f32_e32 v244, v244, v134
	v_fmamk_f32 v244, v244, 0x3c2aaaab, v194
	v_rsq_f32_e32 v244, v244
	s_nop 0
	v_mul_f32_e32 v244, v244, v206
	v_pk_mul_f32 v[88:89], v[88:89], v[244:245] op_sel_hi:[1,0]
	v_pk_mul_f32 v[90:91], v[90:91], v[244:245] op_sel_hi:[1,0]
	v_pk_mul_f32 v[84:85], v[84:85], v[244:245] op_sel_hi:[1,0]
	v_pk_mul_f32 v[86:87], v[86:87], v[244:245] op_sel_hi:[1,0]
	v_cvt_pk_bf16_f32 v88, v88, v89
	v_cvt_pk_bf16_f32 v89, v90, v91
	v_cvt_pk_bf16_f32 v90, v84, v85
	v_cvt_pk_bf16_f32 v91, v86, v87
	global_store_dwordx4 v[248:249], v[88:91], off
	s_mov_b64 vcc, 0xc00
	s_nop 0
	v_lshl_add_u64 v[150:151], v[150:151], 0, vcc
	v_lshl_add_u64 v[248:249], v[248:249], 0, vcc
	v_add_f32_e32 v244, v224, v225
	v_add_f32_e32 v244, v244, v135
	v_fmamk_f32 v244, v244, 0x3c2aaaab, v194
	v_rsq_f32_e32 v244, v244
	s_nop 0
	v_mul_f32_e32 v244, v244, v207
	v_pk_mul_f32 v[76:77], v[76:77], v[244:245] op_sel_hi:[1,0]
	v_pk_mul_f32 v[78:79], v[78:79], v[244:245] op_sel_hi:[1,0]
	v_pk_mul_f32 v[72:73], v[72:73], v[244:245] op_sel_hi:[1,0]
	v_pk_mul_f32 v[74:75], v[74:75], v[244:245] op_sel_hi:[1,0]
	v_cvt_pk_bf16_f32 v76, v76, v77
	v_cvt_pk_bf16_f32 v77, v78, v79
	v_cvt_pk_bf16_f32 v78, v72, v73
	v_cvt_pk_bf16_f32 v79, v74, v75
	global_store_dwordx4 v[150:151], v[76:79], off
	v_add_f32_e32 v244, v226, v227
	v_add_f32_e32 v244, v244, v135
	v_fmamk_f32 v244, v244, 0x3c2aaaab, v194
	v_rsq_f32_e32 v244, v244
	s_nop 0
	v_mul_f32_e32 v244, v244, v207
	v_pk_mul_f32 v[68:69], v[68:69], v[244:245] op_sel_hi:[1,0]
	v_pk_mul_f32 v[70:71], v[70:71], v[244:245] op_sel_hi:[1,0]
	v_pk_mul_f32 v[64:65], v[64:65], v[244:245] op_sel_hi:[1,0]
	v_pk_mul_f32 v[66:67], v[66:67], v[244:245] op_sel_hi:[1,0]
	v_cvt_pk_bf16_f32 v68, v68, v69
	v_cvt_pk_bf16_f32 v69, v70, v71
	v_cvt_pk_bf16_f32 v70, v64, v65
	v_cvt_pk_bf16_f32 v71, v66, v67
	global_store_dwordx4 v[248:249], v[68:71], off
	s_mov_b64 vcc, 0x3c00
	s_nop 0
	v_lshl_add_u64 v[150:151], v[150:151], 0, vcc
	v_lshl_add_u64 v[248:249], v[248:249], 0, vcc
	v_add_f32_e32 v244, v228, v229
	v_add_f32_e32 v244, v244, v136
	v_fmamk_f32 v244, v244, 0x3c2aaaab, v194
	v_rsq_f32_e32 v244, v244
	s_nop 0
	v_mul_f32_e32 v244, v244, v208
	v_pk_mul_f32 v[60:61], v[60:61], v[244:245] op_sel_hi:[1,0]
	v_pk_mul_f32 v[62:63], v[62:63], v[244:245] op_sel_hi:[1,0]
	v_pk_mul_f32 v[56:57], v[56:57], v[244:245] op_sel_hi:[1,0]
	v_pk_mul_f32 v[58:59], v[58:59], v[244:245] op_sel_hi:[1,0]
	v_cvt_pk_bf16_f32 v60, v60, v61
	v_cvt_pk_bf16_f32 v61, v62, v63
	v_cvt_pk_bf16_f32 v62, v56, v57
	v_cvt_pk_bf16_f32 v63, v58, v59
	global_store_dwordx4 v[150:151], v[60:63], off
	v_add_f32_e32 v244, v230, v231
	v_add_f32_e32 v244, v244, v136
	v_fmamk_f32 v244, v244, 0x3c2aaaab, v194
	v_rsq_f32_e32 v244, v244
	s_nop 0
	v_mul_f32_e32 v244, v244, v208
	v_pk_mul_f32 v[52:53], v[52:53], v[244:245] op_sel_hi:[1,0]
	v_pk_mul_f32 v[54:55], v[54:55], v[244:245] op_sel_hi:[1,0]
	v_pk_mul_f32 v[48:49], v[48:49], v[244:245] op_sel_hi:[1,0]
	v_pk_mul_f32 v[50:51], v[50:51], v[244:245] op_sel_hi:[1,0]
	v_cvt_pk_bf16_f32 v52, v52, v53
	v_cvt_pk_bf16_f32 v53, v54, v55
	v_cvt_pk_bf16_f32 v54, v48, v49
	v_cvt_pk_bf16_f32 v55, v50, v51
	global_store_dwordx4 v[248:249], v[52:55], off
	s_mov_b64 vcc, 0xc00
	s_nop 0
	v_lshl_add_u64 v[150:151], v[150:151], 0, vcc
	v_lshl_add_u64 v[248:249], v[248:249], 0, vcc
	v_add_f32_e32 v244, v232, v233
	v_add_f32_e32 v244, v244, v137
	v_fmamk_f32 v244, v244, 0x3c2aaaab, v194
	v_rsq_f32_e32 v244, v244
	s_nop 0
	v_mul_f32_e32 v244, v244, v209
	v_pk_mul_f32 v[44:45], v[44:45], v[244:245] op_sel_hi:[1,0]
	v_pk_mul_f32 v[46:47], v[46:47], v[244:245] op_sel_hi:[1,0]
	v_pk_mul_f32 v[40:41], v[40:41], v[244:245] op_sel_hi:[1,0]
	v_pk_mul_f32 v[42:43], v[42:43], v[244:245] op_sel_hi:[1,0]
	v_cvt_pk_bf16_f32 v44, v44, v45
	v_cvt_pk_bf16_f32 v45, v46, v47
	v_cvt_pk_bf16_f32 v46, v40, v41
	v_cvt_pk_bf16_f32 v47, v42, v43
	global_store_dwordx4 v[150:151], v[44:47], off
	v_add_f32_e32 v244, v234, v235
	v_add_f32_e32 v244, v244, v137
	v_fmamk_f32 v244, v244, 0x3c2aaaab, v194
	v_rsq_f32_e32 v244, v244
	s_nop 0
	v_mul_f32_e32 v244, v244, v209
	v_pk_mul_f32 v[36:37], v[36:37], v[244:245] op_sel_hi:[1,0]
	v_pk_mul_f32 v[38:39], v[38:39], v[244:245] op_sel_hi:[1,0]
	v_pk_mul_f32 v[32:33], v[32:33], v[244:245] op_sel_hi:[1,0]
	v_pk_mul_f32 v[34:35], v[34:35], v[244:245] op_sel_hi:[1,0]
	v_cvt_pk_bf16_f32 v36, v36, v37
	v_cvt_pk_bf16_f32 v37, v38, v39
	v_cvt_pk_bf16_f32 v38, v32, v33
	v_cvt_pk_bf16_f32 v39, v34, v35
	global_store_dwordx4 v[248:249], v[36:39], off
	s_mov_b64 vcc, 0xc00
	s_nop 0
	v_lshl_add_u64 v[150:151], v[150:151], 0, vcc
	v_lshl_add_u64 v[248:249], v[248:249], 0, vcc
	v_add_f32_e32 v244, v236, v237
	v_add_f32_e32 v244, v244, v138
	v_fmamk_f32 v244, v244, 0x3c2aaaab, v194
	v_rsq_f32_e32 v244, v244
	s_nop 0
	v_mul_f32_e32 v244, v244, v210
	v_pk_mul_f32 v[28:29], v[28:29], v[244:245] op_sel_hi:[1,0]
	v_pk_mul_f32 v[30:31], v[30:31], v[244:245] op_sel_hi:[1,0]
	v_pk_mul_f32 v[24:25], v[24:25], v[244:245] op_sel_hi:[1,0]
	v_pk_mul_f32 v[26:27], v[26:27], v[244:245] op_sel_hi:[1,0]
	v_cvt_pk_bf16_f32 v28, v28, v29
	v_cvt_pk_bf16_f32 v29, v30, v31
	v_cvt_pk_bf16_f32 v30, v24, v25
	v_cvt_pk_bf16_f32 v31, v26, v27
	global_store_dwordx4 v[150:151], v[28:31], off
	v_add_f32_e32 v244, v238, v239
	v_add_f32_e32 v244, v244, v138
	v_fmamk_f32 v244, v244, 0x3c2aaaab, v194
	v_rsq_f32_e32 v244, v244
	s_nop 0
	v_mul_f32_e32 v244, v244, v210
	v_pk_mul_f32 v[20:21], v[20:21], v[244:245] op_sel_hi:[1,0]
	v_pk_mul_f32 v[22:23], v[22:23], v[244:245] op_sel_hi:[1,0]
	v_pk_mul_f32 v[16:17], v[16:17], v[244:245] op_sel_hi:[1,0]
	v_pk_mul_f32 v[18:19], v[18:19], v[244:245] op_sel_hi:[1,0]
	v_cvt_pk_bf16_f32 v20, v20, v21
	v_cvt_pk_bf16_f32 v21, v22, v23
	v_cvt_pk_bf16_f32 v22, v16, v17
	v_cvt_pk_bf16_f32 v23, v18, v19
	global_store_dwordx4 v[248:249], v[20:23], off
	s_mov_b64 vcc, 0xc00
	s_nop 0
	v_lshl_add_u64 v[150:151], v[150:151], 0, vcc
	v_lshl_add_u64 v[248:249], v[248:249], 0, vcc
	v_add_f32_e32 v244, v240, v241
	v_add_f32_e32 v244, v244, v139
	v_fmamk_f32 v244, v244, 0x3c2aaaab, v194
	v_rsq_f32_e32 v244, v244
	s_nop 0
	v_mul_f32_e32 v244, v244, v211
	v_pk_mul_f32 v[12:13], v[12:13], v[244:245] op_sel_hi:[1,0]
	v_pk_mul_f32 v[14:15], v[14:15], v[244:245] op_sel_hi:[1,0]
	v_pk_mul_f32 v[8:9], v[8:9], v[244:245] op_sel_hi:[1,0]
	v_pk_mul_f32 v[10:11], v[10:11], v[244:245] op_sel_hi:[1,0]
	v_cvt_pk_bf16_f32 v12, v12, v13
	v_cvt_pk_bf16_f32 v13, v14, v15
	v_cvt_pk_bf16_f32 v14, v8, v9
	v_cvt_pk_bf16_f32 v15, v10, v11
	global_store_dwordx4 v[150:151], v[12:15], off
	v_add_f32_e32 v244, v242, v243
	v_add_f32_e32 v244, v244, v139
	v_fmamk_f32 v244, v244, 0x3c2aaaab, v194
	v_rsq_f32_e32 v244, v244
	s_nop 0
	v_mul_f32_e32 v244, v244, v211
	v_pk_mul_f32 v[4:5], v[4:5], v[244:245] op_sel_hi:[1,0]
	v_pk_mul_f32 v[6:7], v[6:7], v[244:245] op_sel_hi:[1,0]
	v_pk_mul_f32 v[0:1], v[0:1], v[244:245] op_sel_hi:[1,0]
	v_pk_mul_f32 v[2:3], v[2:3], v[244:245] op_sel_hi:[1,0]
	v_cvt_pk_bf16_f32 v4, v4, v5
	v_cvt_pk_bf16_f32 v5, v6, v7
	v_cvt_pk_bf16_f32 v6, v0, v1
	v_cvt_pk_bf16_f32 v7, v2, v3
	global_store_dwordx4 v[248:249], v[4:7], off
	s_branch .Lkv_end
.Lkv_v:
	ds_read_b64 v[212:213], v147 offset:32768
	ds_read_b64 v[214:215], v147 offset:33024
	ds_read_b64 v[216:217], v147 offset:33280
	ds_read_b64 v[218:219], v147 offset:33536
	ds_read_b64 v[220:221], v147 offset:34816
	ds_read_b64 v[222:223], v147 offset:35072
	ds_read_b64 v[224:225], v147 offset:35328
	ds_read_b64 v[226:227], v147 offset:35584
	s_waitcnt lgkmcnt(0)
	v_add_f32_e32 v244, v212, v213
	v_add_f32_e32 v244, v244, v132
	v_fmamk_f32 v244, v244, 0x3c2aaaab, v194
	v_rsq_f32_e32 v244, v244
	v_mov_b32_e32 v80, v204
	v_pk_mul_f32 v[128:129], v[128:129], v[80:81] op_sel_hi:[1,0]
	v_pk_mul_f32 v[130:131], v[130:131], v[80:81] op_sel_hi:[1,0]
	v_pk_mul_f32 v[124:125], v[124:125], v[80:81] op_sel_hi:[1,0]
	v_pk_mul_f32 v[126:127], v[126:127], v[80:81] op_sel_hi:[1,0]
	v_cvt_pk_bf16_f32 v128, v128, v129
	v_cvt_pk_bf16_f32 v129, v130, v131
	v_cvt_pk_bf16_f32 v130, v124, v125
	v_cvt_pk_bf16_f32 v131, v126, v127
	global_store_dwordx4 v[248:249], v[128:131], off
	v_pk_mul_f32 v[120:121], v[120:121], v[80:81] op_sel_hi:[1,0]
	v_pk_mul_f32 v[122:123], v[122:123], v[80:81] op_sel_hi:[1,0]
	v_pk_mul_f32 v[116:117], v[116:117], v[80:81] op_sel_hi:[1,0]
	v_pk_mul_f32 v[118:119], v[118:119], v[80:81] op_sel_hi:[1,0]
	v_cvt_pk_bf16_f32 v120, v120, v121
	v_cvt_pk_bf16_f32 v121, v122, v123
	v_cvt_pk_bf16_f32 v122, v116, v117
	v_cvt_pk_bf16_f32 v123, v118, v119
	global_store_dwordx4 v[248:249], v[120:123], off offset:256
	v_lshlrev_b32_e32 v82, 16, v160
	v_and_b32_e32 v160, 0xffff0000, v160
	v_lshlrev_b32_e32 v83, 16, v161
	v_and_b32_e32 v161, 0xffff0000, v161
	v_lshlrev_b32_e32 v246, 16, v162
	v_and_b32_e32 v162, 0xffff0000, v162
	v_lshlrev_b32_e32 v247, 16, v163
	v_and_b32_e32 v163, 0xffff0000, v163
	v_mul_f32_e32 v82, v82, v244
	v_mul_f32_e32 v160, v160, v244
	v_mul_f32_e32 v83, v83, v244
	v_mul_f32_e32 v161, v161, v244
	v_mul_f32_e32 v246, v246, v244
	v_mul_f32_e32 v162, v162, v244
	v_mul_f32_e32 v247, v247, v244
	v_mul_f32_e32 v163, v163, v244
	v_cvt_pk_bf16_f32 v160, v82, v160
	v_cvt_pk_bf16_f32 v161, v83, v161
	v_cvt_pk_bf16_f32 v162, v246, v162
	v_cvt_pk_bf16_f32 v163, v247, v163
	global_store_dwordx4 v[150:151], v[160:163], off
	s_mov_b64 vcc, 0x8000
	s_nop 0
	v_lshl_add_u64 v[248:249], v[248:249], 0, vcc
	s_mov_b64 vcc, 0xc00
	s_nop 0
	v_lshl_add_u64 v[150:151], v[150:151], 0, vcc
	v_add_f32_e32 v244, v214, v215
	v_add_f32_e32 v244, v244, v133
	v_fmamk_f32 v244, v244, 0x3c2aaaab, v194
	v_rsq_f32_e32 v244, v244
	v_mov_b32_e32 v80, v205
	v_pk_mul_f32 v[112:113], v[112:113], v[80:81] op_sel_hi:[1,0]
	v_pk_mul_f32 v[114:115], v[114:115], v[80:81] op_sel_hi:[1,0]
	v_pk_mul_f32 v[108:109], v[108:109], v[80:81] op_sel_hi:[1,0]
	v_pk_mul_f32 v[110:111], v[110:111], v[80:81] op_sel_hi:[1,0]
	v_cvt_pk_bf16_f32 v112, v112, v113
	v_cvt_pk_bf16_f32 v113, v114, v115
	v_cvt_pk_bf16_f32 v114, v108, v109
	v_cvt_pk_bf16_f32 v115, v110, v111
	global_store_dwordx4 v[248:249], v[112:115], off
	v_pk_mul_f32 v[104:105], v[104:105], v[80:81] op_sel_hi:[1,0]
	v_pk_mul_f32 v[106:107], v[106:107], v[80:81] op_sel_hi:[1,0]
	v_pk_mul_f32 v[100:101], v[100:101], v[80:81] op_sel_hi:[1,0]
	v_pk_mul_f32 v[102:103], v[102:103], v[80:81] op_sel_hi:[1,0]
	v_cvt_pk_bf16_f32 v104, v104, v105
	v_cvt_pk_bf16_f32 v105, v106, v107
	v_cvt_pk_bf16_f32 v106, v100, v101
	v_cvt_pk_bf16_f32 v107, v102, v103
	global_store_dwordx4 v[248:249], v[104:107], off offset:256
	v_lshlrev_b32_e32 v82, 16, v164
	v_and_b32_e32 v164, 0xffff0000, v164
	v_lshlrev_b32_e32 v83, 16, v165
	v_and_b32_e32 v165, 0xffff0000, v165
	v_lshlrev_b32_e32 v246, 16, v166
	v_and_b32_e32 v166, 0xffff0000, v166
	v_lshlrev_b32_e32 v247, 16, v167
	v_and_b32_e32 v167, 0xffff0000, v167
	v_mul_f32_e32 v82, v82, v244
	v_mul_f32_e32 v164, v164, v244
	v_mul_f32_e32 v83, v83, v244
	v_mul_f32_e32 v165, v165, v244
	v_mul_f32_e32 v246, v246, v244
	v_mul_f32_e32 v166, v166, v244
	v_mul_f32_e32 v247, v247, v244
	v_mul_f32_e32 v167, v167, v244
	v_cvt_pk_bf16_f32 v164, v82, v164
	v_cvt_pk_bf16_f32 v165, v83, v165
	v_cvt_pk_bf16_f32 v166, v246, v166
	v_cvt_pk_bf16_f32 v167, v247, v167
	global_store_dwordx4 v[150:151], v[164:167], off
	s_mov_b64 vcc, 0x8000
	s_nop 0
	v_lshl_add_u64 v[248:249], v[248:249], 0, vcc
	s_mov_b64 vcc, 0xc00
	s_nop 0
	v_lshl_add_u64 v[150:151], v[150:151], 0, vcc
	v_add_f32_e32 v244, v216, v217
	v_add_f32_e32 v244, v244, v134
	v_fmamk_f32 v244, v244, 0x3c2aaaab, v194
	v_rsq_f32_e32 v244, v244
	v_mov_b32_e32 v80, v206
	v_pk_mul_f32 v[96:97], v[96:97], v[80:81] op_sel_hi:[1,0]
	v_pk_mul_f32 v[98:99], v[98:99], v[80:81] op_sel_hi:[1,0]
	v_pk_mul_f32 v[92:93], v[92:93], v[80:81] op_sel_hi:[1,0]
	v_pk_mul_f32 v[94:95], v[94:95], v[80:81] op_sel_hi:[1,0]
	v_cvt_pk_bf16_f32 v96, v96, v97
	v_cvt_pk_bf16_f32 v97, v98, v99
	v_cvt_pk_bf16_f32 v98, v92, v93
	v_cvt_pk_bf16_f32 v99, v94, v95
	global_store_dwordx4 v[248:249], v[96:99], off
	v_pk_mul_f32 v[88:89], v[88:89], v[80:81] op_sel_hi:[1,0]
	v_pk_mul_f32 v[90:91], v[90:91], v[80:81] op_sel_hi:[1,0]
	v_pk_mul_f32 v[84:85], v[84:85], v[80:81] op_sel_hi:[1,0]
	v_pk_mul_f32 v[86:87], v[86:87], v[80:81] op_sel_hi:[1,0]
	v_cvt_pk_bf16_f32 v88, v88, v89
	v_cvt_pk_bf16_f32 v89, v90, v91
	v_cvt_pk_bf16_f32 v90, v84, v85
	v_cvt_pk_bf16_f32 v91, v86, v87
	global_store_dwordx4 v[248:249], v[88:91], off offset:256
	v_lshlrev_b32_e32 v82, 16, v168
	v_and_b32_e32 v168, 0xffff0000, v168
	v_lshlrev_b32_e32 v83, 16, v169
	v_and_b32_e32 v169, 0xffff0000, v169
	v_lshlrev_b32_e32 v246, 16, v170
	v_and_b32_e32 v170, 0xffff0000, v170
	v_lshlrev_b32_e32 v247, 16, v171
	v_and_b32_e32 v171, 0xffff0000, v171
	v_mul_f32_e32 v82, v82, v244
	v_mul_f32_e32 v168, v168, v244
	v_mul_f32_e32 v83, v83, v244
	v_mul_f32_e32 v169, v169, v244
	v_mul_f32_e32 v246, v246, v244
	v_mul_f32_e32 v170, v170, v244
	v_mul_f32_e32 v247, v247, v244
	v_mul_f32_e32 v171, v171, v244
	v_cvt_pk_bf16_f32 v168, v82, v168
	v_cvt_pk_bf16_f32 v169, v83, v169
	v_cvt_pk_bf16_f32 v170, v246, v170
	v_cvt_pk_bf16_f32 v171, v247, v171
	global_store_dwordx4 v[150:151], v[168:171], off
	s_mov_b64 vcc, 0x8000
	s_nop 0
	v_lshl_add_u64 v[248:249], v[248:249], 0, vcc
	s_mov_b64 vcc, 0xc00
	s_nop 0
	v_lshl_add_u64 v[150:151], v[150:151], 0, vcc
	v_add_f32_e32 v244, v218, v219
	v_add_f32_e32 v244, v244, v135
	v_fmamk_f32 v244, v244, 0x3c2aaaab, v194
	v_rsq_f32_e32 v244, v244
	v_mov_b32_e32 v80, v207
	v_pk_mul_f32 v[76:77], v[76:77], v[80:81] op_sel_hi:[1,0]
	v_pk_mul_f32 v[78:79], v[78:79], v[80:81] op_sel_hi:[1,0]
	v_pk_mul_f32 v[72:73], v[72:73], v[80:81] op_sel_hi:[1,0]
	v_pk_mul_f32 v[74:75], v[74:75], v[80:81] op_sel_hi:[1,0]
	v_cvt_pk_bf16_f32 v76, v76, v77
	v_cvt_pk_bf16_f32 v77, v78, v79
	v_cvt_pk_bf16_f32 v78, v72, v73
	v_cvt_pk_bf16_f32 v79, v74, v75
	global_store_dwordx4 v[248:249], v[76:79], off
	v_pk_mul_f32 v[68:69], v[68:69], v[80:81] op_sel_hi:[1,0]
	v_pk_mul_f32 v[70:71], v[70:71], v[80:81] op_sel_hi:[1,0]
	v_pk_mul_f32 v[64:65], v[64:65], v[80:81] op_sel_hi:[1,0]
	v_pk_mul_f32 v[66:67], v[66:67], v[80:81] op_sel_hi:[1,0]
	v_cvt_pk_bf16_f32 v68, v68, v69
	v_cvt_pk_bf16_f32 v69, v70, v71
	v_cvt_pk_bf16_f32 v70, v64, v65
	v_cvt_pk_bf16_f32 v71, v66, v67
	global_store_dwordx4 v[248:249], v[68:71], off offset:256
	v_lshlrev_b32_e32 v82, 16, v172
	v_and_b32_e32 v172, 0xffff0000, v172
	v_lshlrev_b32_e32 v83, 16, v173
	v_and_b32_e32 v173, 0xffff0000, v173
	v_lshlrev_b32_e32 v246, 16, v174
	v_and_b32_e32 v174, 0xffff0000, v174
	v_lshlrev_b32_e32 v247, 16, v175
	v_and_b32_e32 v175, 0xffff0000, v175
	v_mul_f32_e32 v82, v82, v244
	v_mul_f32_e32 v172, v172, v244
	v_mul_f32_e32 v83, v83, v244
	v_mul_f32_e32 v173, v173, v244
	v_mul_f32_e32 v246, v246, v244
	v_mul_f32_e32 v174, v174, v244
	v_mul_f32_e32 v247, v247, v244
	v_mul_f32_e32 v175, v175, v244
	v_cvt_pk_bf16_f32 v172, v82, v172
	v_cvt_pk_bf16_f32 v173, v83, v173
	v_cvt_pk_bf16_f32 v174, v246, v174
	v_cvt_pk_bf16_f32 v175, v247, v175
	global_store_dwordx4 v[150:151], v[172:175], off
	s_mov_b64 vcc, 0x28000
	s_nop 0
	v_lshl_add_u64 v[248:249], v[248:249], 0, vcc
	s_mov_b64 vcc, 0x3c00
	s_nop 0
	v_lshl_add_u64 v[150:151], v[150:151], 0, vcc
	v_add_f32_e32 v244, v220, v221
	v_add_f32_e32 v244, v244, v136
	v_fmamk_f32 v244, v244, 0x3c2aaaab, v194
	v_rsq_f32_e32 v244, v244
	v_mov_b32_e32 v80, v208
	v_pk_mul_f32 v[60:61], v[60:61], v[80:81] op_sel_hi:[1,0]
	v_pk_mul_f32 v[62:63], v[62:63], v[80:81] op_sel_hi:[1,0]
	v_pk_mul_f32 v[56:57], v[56:57], v[80:81] op_sel_hi:[1,0]
	v_pk_mul_f32 v[58:59], v[58:59], v[80:81] op_sel_hi:[1,0]
	v_cvt_pk_bf16_f32 v60, v60, v61
	v_cvt_pk_bf16_f32 v61, v62, v63
	v_cvt_pk_bf16_f32 v62, v56, v57
	v_cvt_pk_bf16_f32 v63, v58, v59
	global_store_dwordx4 v[248:249], v[60:63], off
	v_pk_mul_f32 v[52:53], v[52:53], v[80:81] op_sel_hi:[1,0]
	v_pk_mul_f32 v[54:55], v[54:55], v[80:81] op_sel_hi:[1,0]
	v_pk_mul_f32 v[48:49], v[48:49], v[80:81] op_sel_hi:[1,0]
	v_pk_mul_f32 v[50:51], v[50:51], v[80:81] op_sel_hi:[1,0]
	v_cvt_pk_bf16_f32 v52, v52, v53
	v_cvt_pk_bf16_f32 v53, v54, v55
	v_cvt_pk_bf16_f32 v54, v48, v49
	v_cvt_pk_bf16_f32 v55, v50, v51
	global_store_dwordx4 v[248:249], v[52:55], off offset:256
	v_lshlrev_b32_e32 v82, 16, v176
	v_and_b32_e32 v176, 0xffff0000, v176
	v_lshlrev_b32_e32 v83, 16, v177
	v_and_b32_e32 v177, 0xffff0000, v177
	v_lshlrev_b32_e32 v246, 16, v178
	v_and_b32_e32 v178, 0xffff0000, v178
	v_lshlrev_b32_e32 v247, 16, v179
	v_and_b32_e32 v179, 0xffff0000, v179
	v_mul_f32_e32 v82, v82, v244
	v_mul_f32_e32 v176, v176, v244
	v_mul_f32_e32 v83, v83, v244
	v_mul_f32_e32 v177, v177, v244
	v_mul_f32_e32 v246, v246, v244
	v_mul_f32_e32 v178, v178, v244
	v_mul_f32_e32 v247, v247, v244
	v_mul_f32_e32 v179, v179, v244
	v_cvt_pk_bf16_f32 v176, v82, v176
	v_cvt_pk_bf16_f32 v177, v83, v177
	v_cvt_pk_bf16_f32 v178, v246, v178
	v_cvt_pk_bf16_f32 v179, v247, v179
	global_store_dwordx4 v[150:151], v[176:179], off
	s_mov_b64 vcc, 0x8000
	s_nop 0
	v_lshl_add_u64 v[248:249], v[248:249], 0, vcc
	s_mov_b64 vcc, 0xc00
	s_nop 0
	v_lshl_add_u64 v[150:151], v[150:151], 0, vcc
	v_add_f32_e32 v244, v222, v223
	v_add_f32_e32 v244, v244, v137
	v_fmamk_f32 v244, v244, 0x3c2aaaab, v194
	v_rsq_f32_e32 v244, v244
	v_mov_b32_e32 v80, v209
	v_pk_mul_f32 v[44:45], v[44:45], v[80:81] op_sel_hi:[1,0]
	v_pk_mul_f32 v[46:47], v[46:47], v[80:81] op_sel_hi:[1,0]
	v_pk_mul_f32 v[40:41], v[40:41], v[80:81] op_sel_hi:[1,0]
	v_pk_mul_f32 v[42:43], v[42:43], v[80:81] op_sel_hi:[1,0]
	v_cvt_pk_bf16_f32 v44, v44, v45
	v_cvt_pk_bf16_f32 v45, v46, v47
	v_cvt_pk_bf16_f32 v46, v40, v41
	v_cvt_pk_bf16_f32 v47, v42, v43
	global_store_dwordx4 v[248:249], v[44:47], off
	v_pk_mul_f32 v[36:37], v[36:37], v[80:81] op_sel_hi:[1,0]
	v_pk_mul_f32 v[38:39], v[38:39], v[80:81] op_sel_hi:[1,0]
	v_pk_mul_f32 v[32:33], v[32:33], v[80:81] op_sel_hi:[1,0]
	v_pk_mul_f32 v[34:35], v[34:35], v[80:81] op_sel_hi:[1,0]
	v_cvt_pk_bf16_f32 v36, v36, v37
	v_cvt_pk_bf16_f32 v37, v38, v39
	v_cvt_pk_bf16_f32 v38, v32, v33
	v_cvt_pk_bf16_f32 v39, v34, v35
	global_store_dwordx4 v[248:249], v[36:39], off offset:256
	v_lshlrev_b32_e32 v82, 16, v180
	v_and_b32_e32 v180, 0xffff0000, v180
	v_lshlrev_b32_e32 v83, 16, v181
	v_and_b32_e32 v181, 0xffff0000, v181
	v_lshlrev_b32_e32 v246, 16, v182
	v_and_b32_e32 v182, 0xffff0000, v182
	v_lshlrev_b32_e32 v247, 16, v183
	v_and_b32_e32 v183, 0xffff0000, v183
	v_mul_f32_e32 v82, v82, v244
	v_mul_f32_e32 v180, v180, v244
	v_mul_f32_e32 v83, v83, v244
	v_mul_f32_e32 v181, v181, v244
	v_mul_f32_e32 v246, v246, v244
	v_mul_f32_e32 v182, v182, v244
	v_mul_f32_e32 v247, v247, v244
	v_mul_f32_e32 v183, v183, v244
	v_cvt_pk_bf16_f32 v180, v82, v180
	v_cvt_pk_bf16_f32 v181, v83, v181
	v_cvt_pk_bf16_f32 v182, v246, v182
	v_cvt_pk_bf16_f32 v183, v247, v183
	global_store_dwordx4 v[150:151], v[180:183], off
	s_mov_b64 vcc, 0x8000
	s_nop 0
	v_lshl_add_u64 v[248:249], v[248:249], 0, vcc
	s_mov_b64 vcc, 0xc00
	s_nop 0
	v_lshl_add_u64 v[150:151], v[150:151], 0, vcc
	v_add_f32_e32 v244, v224, v225
	v_add_f32_e32 v244, v244, v138
	v_fmamk_f32 v244, v244, 0x3c2aaaab, v194
	v_rsq_f32_e32 v244, v244
	v_mov_b32_e32 v80, v210
	v_pk_mul_f32 v[28:29], v[28:29], v[80:81] op_sel_hi:[1,0]
	v_pk_mul_f32 v[30:31], v[30:31], v[80:81] op_sel_hi:[1,0]
	v_pk_mul_f32 v[24:25], v[24:25], v[80:81] op_sel_hi:[1,0]
	v_pk_mul_f32 v[26:27], v[26:27], v[80:81] op_sel_hi:[1,0]
	v_cvt_pk_bf16_f32 v28, v28, v29
	v_cvt_pk_bf16_f32 v29, v30, v31
	v_cvt_pk_bf16_f32 v30, v24, v25
	v_cvt_pk_bf16_f32 v31, v26, v27
	global_store_dwordx4 v[248:249], v[28:31], off
	v_pk_mul_f32 v[20:21], v[20:21], v[80:81] op_sel_hi:[1,0]
	v_pk_mul_f32 v[22:23], v[22:23], v[80:81] op_sel_hi:[1,0]
	v_pk_mul_f32 v[16:17], v[16:17], v[80:81] op_sel_hi:[1,0]
	v_pk_mul_f32 v[18:19], v[18:19], v[80:81] op_sel_hi:[1,0]
	v_cvt_pk_bf16_f32 v20, v20, v21
	v_cvt_pk_bf16_f32 v21, v22, v23
	v_cvt_pk_bf16_f32 v22, v16, v17
	v_cvt_pk_bf16_f32 v23, v18, v19
	global_store_dwordx4 v[248:249], v[20:23], off offset:256
	v_lshlrev_b32_e32 v82, 16, v184
	v_and_b32_e32 v184, 0xffff0000, v184
	v_lshlrev_b32_e32 v83, 16, v185
	v_and_b32_e32 v185, 0xffff0000, v185
	v_lshlrev_b32_e32 v246, 16, v186
	v_and_b32_e32 v186, 0xffff0000, v186
	v_lshlrev_b32_e32 v247, 16, v187
	v_and_b32_e32 v187, 0xffff0000, v187
	v_mul_f32_e32 v82, v82, v244
	v_mul_f32_e32 v184, v184, v244
	v_mul_f32_e32 v83, v83, v244
	v_mul_f32_e32 v185, v185, v244
	v_mul_f32_e32 v246, v246, v244
	v_mul_f32_e32 v186, v186, v244
	v_mul_f32_e32 v247, v247, v244
	v_mul_f32_e32 v187, v187, v244
	v_cvt_pk_bf16_f32 v184, v82, v184
	v_cvt_pk_bf16_f32 v185, v83, v185
	v_cvt_pk_bf16_f32 v186, v246, v186
	v_cvt_pk_bf16_f32 v187, v247, v187
	global_store_dwordx4 v[150:151], v[184:187], off
	s_mov_b64 vcc, 0x8000
	s_nop 0
	v_lshl_add_u64 v[248:249], v[248:249], 0, vcc
	s_mov_b64 vcc, 0xc00
	s_nop 0
	v_lshl_add_u64 v[150:151], v[150:151], 0, vcc
	v_add_f32_e32 v244, v226, v227
	v_add_f32_e32 v244, v244, v139
	v_fmamk_f32 v244, v244, 0x3c2aaaab, v194
	v_rsq_f32_e32 v244, v244
	v_mov_b32_e32 v80, v211
	v_pk_mul_f32 v[12:13], v[12:13], v[80:81] op_sel_hi:[1,0]
	v_pk_mul_f32 v[14:15], v[14:15], v[80:81] op_sel_hi:[1,0]
	v_pk_mul_f32 v[8:9], v[8:9], v[80:81] op_sel_hi:[1,0]
	v_pk_mul_f32 v[10:11], v[10:11], v[80:81] op_sel_hi:[1,0]
	v_cvt_pk_bf16_f32 v12, v12, v13
	v_cvt_pk_bf16_f32 v13, v14, v15
	v_cvt_pk_bf16_f32 v14, v8, v9
	v_cvt_pk_bf16_f32 v15, v10, v11
	global_store_dwordx4 v[248:249], v[12:15], off
	v_pk_mul_f32 v[4:5], v[4:5], v[80:81] op_sel_hi:[1,0]
	v_pk_mul_f32 v[6:7], v[6:7], v[80:81] op_sel_hi:[1,0]
	v_pk_mul_f32 v[0:1], v[0:1], v[80:81] op_sel_hi:[1,0]
	v_pk_mul_f32 v[2:3], v[2:3], v[80:81] op_sel_hi:[1,0]
	v_cvt_pk_bf16_f32 v4, v4, v5
	v_cvt_pk_bf16_f32 v5, v6, v7
	v_cvt_pk_bf16_f32 v6, v0, v1
	v_cvt_pk_bf16_f32 v7, v2, v3
	global_store_dwordx4 v[248:249], v[4:7], off offset:256
	v_lshlrev_b32_e32 v82, 16, v188
	v_and_b32_e32 v188, 0xffff0000, v188
	v_lshlrev_b32_e32 v83, 16, v189
	v_and_b32_e32 v189, 0xffff0000, v189
	v_lshlrev_b32_e32 v246, 16, v190
	v_and_b32_e32 v190, 0xffff0000, v190
	v_lshlrev_b32_e32 v247, 16, v191
	v_and_b32_e32 v191, 0xffff0000, v191
	v_mul_f32_e32 v82, v82, v244
	v_mul_f32_e32 v188, v188, v244
	v_mul_f32_e32 v83, v83, v244
	v_mul_f32_e32 v189, v189, v244
	v_mul_f32_e32 v246, v246, v244
	v_mul_f32_e32 v190, v190, v244
	v_mul_f32_e32 v247, v247, v244
	v_mul_f32_e32 v191, v191, v244
	v_cvt_pk_bf16_f32 v188, v82, v188
	v_cvt_pk_bf16_f32 v189, v83, v189
	v_cvt_pk_bf16_f32 v190, v246, v190
	v_cvt_pk_bf16_f32 v191, v247, v191
	global_store_dwordx4 v[150:151], v[188:191], off
.Lkv_end:
	s_mov_b64 s[0:1], exec
